# softmax exps software-pipelined: exp of tile t+1 done in place inside the P.V MFMA block of step t
# speedup vs baseline: 1.0178x; 1.0178x over previous
.LBB0_279:
	v_bitop3_b32 v17, v17, 15, v18 bitop3:0xc8
	s_waitcnt lgkmcnt(0)
	v_bitop3_b32 v2, v14, v17, 2 bitop3:0x36
	v_lshl_add_u32 v2, v2, 4, v0
	v_add_u32_e32 v204, 0, v2
	ds_read_b128 v[2:5], v204
	ds_read_b128 v[6:9], v204 offset:8192
	v_and_b32_e32 v203, 63, v10
	v_and_b32_e32 v10, 7, v11
	v_lshlrev_b64 v[186:187], 10, v[12:13]
	s_waitcnt lgkmcnt(1)
	v_mfma_f32_32x32x16_bf16 v[66:81], v[2:5], v[134:137], v[66:81]
	v_bitop3_b32 v2, v14, v17, 4 bitop3:0x36
	v_lshl_add_u32 v2, v2, 4, v0
	v_add_u32_e32 v205, 0, v2
	ds_read_b128 v[2:5], v205
	v_bitop3_b32 v19, v198, v11, 7 bitop3:0x78
	v_bitop3_b32 v20, v198, v10, 2 bitop3:0x36
	v_bitop3_b32 v21, v198, v10, 4 bitop3:0x36
	s_waitcnt lgkmcnt(1)
	v_mfma_f32_32x32x16_bf16 v[82:97], v[6:9], v[134:137], v[82:97]
	v_bitop3_b32 v6, v14, v17, 6 bitop3:0x36
	v_lshl_add_u32 v0, v6, 4, v0
	ds_read_b128 v[6:9], v205 offset:8192
	v_add_u32_e32 v206, 0, v0
	v_bitop3_b32 v14, v198, v10, 6 bitop3:0x36
	v_lshlrev_b32_e32 v18, 7, v199
	v_sub_u32_e32 v0, v15, v16
	s_waitcnt lgkmcnt(1)
	v_mfma_f32_32x32x16_bf16 v[66:81], v[2:5], v[138:141], v[66:81]
	ds_read_b128 v[2:5], v206
	ds_read_b128 v[10:13], v206 offset:8192
	v_lshl_or_b32 v16, v19, 4, v18
	v_lshl_or_b32 v17, v20, 4, v18
	v_lshl_or_b32 v19, v21, 4, v18
	v_lshl_or_b32 v18, v14, 4, v18
	v_mov_b32_e32 v14, v1
	v_mov_b32_e32 v15, v1
	s_waitcnt lgkmcnt(2)
	v_mfma_f32_32x32x16_bf16 v[82:97], v[6:9], v[138:141], v[82:97]
	v_lshl_add_u32 v207, v0, 2, s68
	v_mov_b32_e32 v0, v1
	v_mov_b32_e32 v6, v1
	v_mov_b32_e32 v7, v1
	v_mov_b32_e32 v8, v1
	v_mov_b32_e32 v9, v1
	v_add_u32_e32 v210, 0, v19
	s_waitcnt lgkmcnt(1)
	v_mfma_f32_32x32x16_bf16 v[66:81], v[2:5], v[142:145], v[66:81]
	v_mov_b32_e32 v2, v1
	v_mov_b32_e32 v3, v1
	v_mov_b32_e32 v4, v1
	v_mov_b32_e32 v5, v1
	v_add_u32_e32 v212, 0, v18
	v_add_u32_e32 v208, 0, v16
	v_add_u32_e32 v209, 0, v17
	s_waitcnt lgkmcnt(0)
	v_mfma_f32_32x32x16_bf16 v[82:97], v[10:13], v[142:145], v[82:97]
	v_mov_b32_e32 v10, v1
	v_mov_b32_e32 v11, v1
	v_mov_b32_e32 v12, v1
	v_mov_b32_e32 v13, v1
	v_mov_b64_e32 v[64:65], v[14:15]
	v_mov_b64_e32 v[48:49], v[14:15]
	v_mov_b64_e32 v[32:33], v[14:15]
	v_mov_b64_e32 v[62:63], v[12:13]
	v_mov_b64_e32 v[60:61], v[10:11]
	v_mov_b64_e32 v[58:59], v[8:9]
	v_mov_b64_e32 v[56:57], v[6:7]
	v_mov_b64_e32 v[54:55], v[4:5]
	v_mov_b64_e32 v[52:53], v[2:3]
	v_mov_b64_e32 v[50:51], v[0:1]
	v_mov_b64_e32 v[46:47], v[12:13]
	v_mov_b64_e32 v[44:45], v[10:11]
	v_mov_b64_e32 v[42:43], v[8:9]
	v_mov_b64_e32 v[40:41], v[6:7]
	v_mov_b64_e32 v[38:39], v[4:5]
	v_mov_b64_e32 v[36:37], v[2:3]
	v_mov_b64_e32 v[34:35], v[0:1]
	v_mov_b64_e32 v[30:31], v[12:13]
	v_mov_b64_e32 v[28:29], v[10:11]
	v_mov_b64_e32 v[26:27], v[8:9]
	v_mov_b64_e32 v[24:25], v[6:7]
	v_mov_b64_e32 v[22:23], v[4:5]
	v_mov_b64_e32 v[20:21], v[2:3]
	v_mov_b64_e32 v[18:19], v[0:1]
	v_mov_b64_e32 v[16:17], v[14:15]
	s_mov_b32 s14, 1
	v_mov_b32_e32 v213, 0
	s_mov_b32 s76, -2
	s_mov_b32 s77, s82
	s_mov_b32 s78, s66
	v_mov_b64_e32 v[14:15], v[12:13]
	v_mov_b64_e32 v[12:13], v[10:11]
	v_mov_b64_e32 v[10:11], v[8:9]
	v_mov_b64_e32 v[8:9], v[6:7]
	v_mov_b64_e32 v[6:7], v[4:5]
	v_mov_b64_e32 v[4:5], v[2:3]
	v_mov_b64_e32 v[2:3], v[0:1]
	v_exp_f32_e32 v66, v66
	v_exp_f32_e32 v67, v67
	v_exp_f32_e32 v68, v68
	v_exp_f32_e32 v69, v69
	v_exp_f32_e32 v70, v70
	v_exp_f32_e32 v71, v71
	v_exp_f32_e32 v72, v72
	v_exp_f32_e32 v73, v73
	v_exp_f32_e32 v74, v74
	v_exp_f32_e32 v75, v75
	v_exp_f32_e32 v76, v76
	v_exp_f32_e32 v77, v77
	v_exp_f32_e32 v78, v78
	v_exp_f32_e32 v79, v79
	v_exp_f32_e32 v80, v80
	v_exp_f32_e32 v81, v81
	v_exp_f32_e32 v82, v82
	v_exp_f32_e32 v83, v83
	v_exp_f32_e32 v84, v84
	v_exp_f32_e32 v85, v85
	v_exp_f32_e32 v86, v86
	v_exp_f32_e32 v87, v87
	v_exp_f32_e32 v88, v88
	v_exp_f32_e32 v89, v89
	v_exp_f32_e32 v90, v90
	v_exp_f32_e32 v91, v91
	v_exp_f32_e32 v92, v92
	v_exp_f32_e32 v93, v93
	v_exp_f32_e32 v94, v94
	v_exp_f32_e32 v95, v95
	v_exp_f32_e32 v96, v96
	v_exp_f32_e32 v97, v97
	s_barrier
	s_branch .LBB0_281
.LBB0_280:
	s_waitcnt lgkmcnt(5)
	v_mfma_f32_32x32x16_bf16 v[66:81], v[166:169], v[134:137], v[66:81]
	s_waitcnt lgkmcnt(4)
	v_mfma_f32_32x32x16_bf16 v[82:97], v[162:165], v[134:137], v[82:97]
	s_waitcnt lgkmcnt(3)
	v_mfma_f32_32x32x16_bf16 v[66:81], v[158:161], v[138:141], v[66:81]
	s_waitcnt lgkmcnt(2)
	v_mfma_f32_32x32x16_bf16 v[82:97], v[154:157], v[138:141], v[82:97]
	s_waitcnt lgkmcnt(1)
	v_mfma_f32_32x32x16_bf16 v[66:81], v[150:153], v[142:145], v[66:81]
	s_waitcnt lgkmcnt(0)
	v_mfma_f32_32x32x16_bf16 v[82:97], v[146:149], v[142:145], v[82:97]
	s_and_b32 s0, s77, 0x3f0000
	s_lshl_b32 s22, s0, 1
	s_mov_b32 m0, s73
	v_lshl_add_u64 v[164:165], v[188:189], 0, s[22:23]
	global_load_lds_dwordx4 v[164:165], off
	v_lshl_add_u64 v[164:165], v[192:193], 0, s[22:23]
	s_mov_b32 m0, s31
	s_lshl_b32 s22, s15, 1
	global_load_lds_dwordx4 v[164:165], off
	v_lshl_add_u64 v[164:165], v[190:191], 0, s[22:23]
	s_mov_b32 m0, s71
	global_load_lds_dwordx4 v[164:165], off
	v_lshl_add_u64 v[164:165], v[194:195], 0, s[22:23]
	s_mov_b32 m0, s72
	s_nop 0
	global_load_lds_dwordx4 v[164:165], off
	v_pk_add_f32 v[146:147], v[114:115], v[98:99]
	v_pk_add_f32 v[148:149], v[116:117], v[100:101]
	v_pk_add_f32 v[150:151], v[118:119], v[102:103]
	v_pk_add_f32 v[152:153], v[120:121], v[104:105]
	v_pk_add_f32 v[154:155], v[122:123], v[106:107]
	v_pk_add_f32 v[156:157], v[124:125], v[108:109]
	v_pk_add_f32 v[158:159], v[126:127], v[110:111]
	v_pk_add_f32 v[160:161], v[128:129], v[112:113]
	v_pk_add_f32 v[146:147], v[146:147], v[148:149]
	v_pk_add_f32 v[150:151], v[150:151], v[152:153]
	v_pk_add_f32 v[154:155], v[154:155], v[156:157]
	v_pk_add_f32 v[158:159], v[158:159], v[160:161]
	v_pk_add_f32 v[146:147], v[146:147], v[150:151]
	v_pk_add_f32 v[154:155], v[154:155], v[158:159]
	v_cvt_pk_bf16_f32 v113, v112, v113
	v_cvt_pk_bf16_f32 v112, v110, v111
	v_cvt_pk_bf16_f32 v111, v108, v109
	v_cvt_pk_bf16_f32 v110, v106, v107
	v_pk_add_f32 v[146:147], v[146:147], v[154:155]
	v_cvt_pk_bf16_f32 v109, v104, v105
	v_cvt_pk_bf16_f32 v108, v102, v103
	v_cvt_pk_bf16_f32 v107, v100, v101
	v_cvt_pk_bf16_f32 v106, v98, v99
	v_cvt_pk_bf16_f32 v98, v114, v115
	v_cvt_pk_bf16_f32 v99, v116, v117
	v_cvt_pk_bf16_f32 v100, v118, v119
	v_cvt_pk_bf16_f32 v101, v120, v121
	v_cvt_pk_bf16_f32 v102, v122, v123
	v_cvt_pk_bf16_f32 v103, v124, v125
	v_cvt_pk_bf16_f32 v104, v126, v127
	v_cvt_pk_bf16_f32 v105, v128, v129
	v_add_f32_e32 v162, v146, v147
	s_nop 0
	v_add_f32_e32 v213, v162, v0
	ds_read_b128 v[114:117], v208 offset:49152
	ds_read_b128 v[118:121], v208 offset:53248
	ds_read_b128 v[122:125], v208 offset:57344
	ds_read_b128 v[126:129], v208 offset:61440
	ds_read_b128 v[150:153], v209 offset:53248
	ds_read_b128 v[146:149], v209 offset:49152
	ds_read_b128 v[154:157], v209 offset:57344
	ds_read_b128 v[158:161], v209 offset:61440
	s_waitcnt lgkmcnt(0)
	v_mfma_f32_32x32x16_bf16 v[50:65], v[98:101], v[114:117], v[50:65]
	ds_read_b128 v[114:117], v210 offset:53248
	v_exp_f32_e32 v66, v66
	v_exp_f32_e32 v67, v67
	v_mfma_f32_32x32x16_bf16 v[34:49], v[98:101], v[118:121], v[34:49]
	ds_read_b128 v[118:121], v210 offset:57344
	v_exp_f32_e32 v68, v68
	v_exp_f32_e32 v69, v69
	v_mfma_f32_32x32x16_bf16 v[18:33], v[98:101], v[122:125], v[18:33]
	ds_read_b128 v[122:125], v210 offset:61440
	v_exp_f32_e32 v70, v70
	v_exp_f32_e32 v71, v71
	v_mfma_f32_32x32x16_bf16 v[2:17], v[98:101], v[126:129], v[2:17]
	ds_read_b128 v[98:101], v210 offset:49152
	v_exp_f32_e32 v72, v72
	v_exp_f32_e32 v73, v73
	v_mfma_f32_32x32x16_bf16 v[50:65], v[102:105], v[146:149], v[50:65]
	ds_read_b128 v[126:129], v212 offset:53248
	v_exp_f32_e32 v74, v74
	v_exp_f32_e32 v75, v75
	v_mfma_f32_32x32x16_bf16 v[34:49], v[102:105], v[150:153], v[34:49]
	ds_read_b128 v[146:149], v212 offset:57344
	v_exp_f32_e32 v76, v76
	v_exp_f32_e32 v77, v77
	v_mfma_f32_32x32x16_bf16 v[18:33], v[102:105], v[154:157], v[18:33]
	ds_read_b128 v[150:153], v212 offset:61440
	v_exp_f32_e32 v78, v78
	v_exp_f32_e32 v79, v79
	v_mfma_f32_32x32x16_bf16 v[2:17], v[102:105], v[158:161], v[2:17]
	ds_read_b128 v[102:105], v212 offset:49152
	v_exp_f32_e32 v80, v80
	v_exp_f32_e32 v81, v81
	s_waitcnt lgkmcnt(0)
	v_mfma_f32_32x32x16_bf16 v[50:65], v[106:109], v[98:101], v[50:65]
	v_exp_f32_e32 v82, v82
	v_exp_f32_e32 v83, v83
	v_mfma_f32_32x32x16_bf16 v[34:49], v[106:109], v[114:117], v[34:49]
	v_exp_f32_e32 v84, v84
	v_exp_f32_e32 v85, v85
	v_mfma_f32_32x32x16_bf16 v[18:33], v[106:109], v[118:121], v[18:33]
	v_exp_f32_e32 v86, v86
	v_exp_f32_e32 v87, v87
	v_mfma_f32_32x32x16_bf16 v[2:17], v[106:109], v[122:125], v[2:17]
	v_exp_f32_e32 v88, v88
	v_exp_f32_e32 v89, v89
	v_mfma_f32_32x32x16_bf16 v[50:65], v[110:113], v[102:105], v[50:65]
	v_exp_f32_e32 v90, v90
	v_exp_f32_e32 v91, v91
	v_mfma_f32_32x32x16_bf16 v[34:49], v[110:113], v[126:129], v[34:49]
	v_exp_f32_e32 v92, v92
	v_exp_f32_e32 v93, v93
	v_mfma_f32_32x32x16_bf16 v[18:33], v[110:113], v[146:149], v[18:33]
	v_exp_f32_e32 v94, v94
	v_exp_f32_e32 v95, v95
	v_mfma_f32_32x32x16_bf16 v[2:17], v[110:113], v[150:153], v[2:17]
	v_exp_f32_e32 v96, v96
	v_exp_f32_e32 v97, v97
	s_waitcnt vmcnt(0)
	s_add_i32 s76, s76, 2
	s_add_i32 s77, s77, 0x20000
	s_cmp_gt_u32 s76, 61
	s_waitcnt vmcnt(0)
	s_barrier
	s_cbranch_scc1 .LBB0_295

.LBB0_288:
	s_waitcnt lgkmcnt(5)
	v_mfma_f32_32x32x16_bf16 v[114:129], v[166:169], v[134:137], v[114:129]
	s_waitcnt lgkmcnt(4)
	v_mfma_f32_32x32x16_bf16 v[98:113], v[162:165], v[134:137], v[98:113]
	s_waitcnt lgkmcnt(3)
	v_mfma_f32_32x32x16_bf16 v[114:129], v[158:161], v[138:141], v[114:129]
	s_waitcnt lgkmcnt(2)
	v_mfma_f32_32x32x16_bf16 v[98:113], v[154:157], v[138:141], v[98:113]
	s_waitcnt lgkmcnt(1)
	v_mfma_f32_32x32x16_bf16 v[114:129], v[150:153], v[142:145], v[114:129]
	s_waitcnt lgkmcnt(0)
	v_mfma_f32_32x32x16_bf16 v[98:113], v[146:149], v[142:145], v[98:113]
	s_add_i32 s14, s77, 0xffff0000
	s_and_b32 s14, s14, 0x3e0000
	s_lshl_b32 s22, s14, 1
	s_mov_b32 m0, s70
	v_lshl_add_u64 v[164:165], v[188:189], 0, s[22:23]
	global_load_lds_dwordx4 v[164:165], off
	v_lshl_add_u64 v[164:165], v[192:193], 0, s[22:23]
	s_mov_b32 m0, s29
	s_lshl_b32 s22, s80, 1
	global_load_lds_dwordx4 v[164:165], off
	v_lshl_add_u64 v[164:165], v[190:191], 0, s[22:23]
	s_add_i32 m0, s70, 0xc000
	global_load_lds_dwordx4 v[164:165], off
	v_lshl_add_u64 v[164:165], v[194:195], 0, s[22:23]
	s_add_i32 m0, s70, 0xc400
	s_nop 0
	global_load_lds_dwordx4 v[164:165], off
	v_pk_add_f32 v[146:147], v[66:67], v[82:83]
	v_pk_add_f32 v[148:149], v[68:69], v[84:85]
	v_pk_add_f32 v[150:151], v[70:71], v[86:87]
	v_pk_add_f32 v[152:153], v[72:73], v[88:89]
	v_pk_add_f32 v[154:155], v[74:75], v[90:91]
	v_pk_add_f32 v[156:157], v[76:77], v[92:93]
	v_pk_add_f32 v[158:159], v[78:79], v[94:95]
	v_pk_add_f32 v[160:161], v[80:81], v[96:97]
	v_pk_add_f32 v[146:147], v[146:147], v[148:149]
	v_pk_add_f32 v[150:151], v[150:151], v[152:153]
	v_pk_add_f32 v[154:155], v[154:155], v[156:157]
	v_pk_add_f32 v[158:159], v[158:159], v[160:161]
	v_pk_add_f32 v[146:147], v[146:147], v[150:151]
	v_pk_add_f32 v[154:155], v[154:155], v[158:159]
	v_cvt_pk_bf16_f32 v66, v66, v67
	v_cvt_pk_bf16_f32 v67, v68, v69
	v_cvt_pk_bf16_f32 v68, v70, v71
	v_cvt_pk_bf16_f32 v69, v72, v73
	v_pk_add_f32 v[146:147], v[146:147], v[154:155]
	v_cvt_pk_bf16_f32 v70, v74, v75
	v_cvt_pk_bf16_f32 v71, v76, v77
	v_cvt_pk_bf16_f32 v72, v78, v79
	v_cvt_pk_bf16_f32 v73, v80, v81
	v_cvt_pk_bf16_f32 v74, v82, v83
	v_cvt_pk_bf16_f32 v75, v84, v85
	v_cvt_pk_bf16_f32 v76, v86, v87
	v_cvt_pk_bf16_f32 v77, v88, v89
	v_cvt_pk_bf16_f32 v78, v90, v91
	v_cvt_pk_bf16_f32 v79, v92, v93
	v_cvt_pk_bf16_f32 v80, v94, v95
	v_cvt_pk_bf16_f32 v81, v96, v97
	v_add_f32_e32 v162, v146, v147
	s_nop 0
	v_add_f32_e32 v0, v162, v213
	ds_read_b128 v[82:85], v208 offset:32768
	ds_read_b128 v[86:89], v208 offset:36864
	ds_read_b128 v[90:93], v208 offset:40960
	ds_read_b128 v[94:97], v208 offset:45056
	ds_read_b128 v[146:149], v209 offset:32768
	ds_read_b128 v[150:153], v209 offset:36864
	ds_read_b128 v[154:157], v209 offset:40960
	ds_read_b128 v[158:161], v209 offset:45056
	s_waitcnt lgkmcnt(0)
	v_mfma_f32_32x32x16_bf16 v[50:65], v[66:69], v[82:85], v[50:65]
	ds_read_b128 v[82:85], v210 offset:32768
	v_exp_f32_e32 v114, v114
	v_exp_f32_e32 v115, v115
	v_mfma_f32_32x32x16_bf16 v[34:49], v[66:69], v[86:89], v[34:49]
	ds_read_b128 v[86:89], v210 offset:36864
	v_exp_f32_e32 v116, v116
	v_exp_f32_e32 v117, v117
	v_mfma_f32_32x32x16_bf16 v[18:33], v[66:69], v[90:93], v[18:33]
	ds_read_b128 v[90:93], v210 offset:40960
	v_exp_f32_e32 v118, v118
	v_exp_f32_e32 v119, v119
	v_mfma_f32_32x32x16_bf16 v[2:17], v[66:69], v[94:97], v[2:17]
	ds_read_b128 v[66:69], v210 offset:45056
	v_exp_f32_e32 v120, v120
	v_exp_f32_e32 v121, v121
	v_mfma_f32_32x32x16_bf16 v[50:65], v[70:73], v[146:149], v[50:65]
	ds_read_b128 v[94:97], v212 offset:32768
	v_exp_f32_e32 v122, v122
	v_exp_f32_e32 v123, v123
	v_mfma_f32_32x32x16_bf16 v[34:49], v[70:73], v[150:153], v[34:49]
	ds_read_b128 v[146:149], v212 offset:36864
	v_exp_f32_e32 v124, v124
	v_exp_f32_e32 v125, v125
	v_mfma_f32_32x32x16_bf16 v[18:33], v[70:73], v[154:157], v[18:33]
	ds_read_b128 v[150:153], v212 offset:40960
	v_exp_f32_e32 v126, v126
	v_exp_f32_e32 v127, v127
	v_mfma_f32_32x32x16_bf16 v[2:17], v[70:73], v[158:161], v[2:17]
	ds_read_b128 v[70:73], v212 offset:45056
	v_exp_f32_e32 v128, v128
	v_exp_f32_e32 v129, v129
	s_waitcnt lgkmcnt(0)
	v_mfma_f32_32x32x16_bf16 v[50:65], v[74:77], v[82:85], v[50:65]
	v_exp_f32_e32 v98, v98
	v_exp_f32_e32 v99, v99
	v_mfma_f32_32x32x16_bf16 v[34:49], v[74:77], v[86:89], v[34:49]
	v_exp_f32_e32 v100, v100
	v_exp_f32_e32 v101, v101
	v_mfma_f32_32x32x16_bf16 v[18:33], v[74:77], v[90:93], v[18:33]
	v_exp_f32_e32 v102, v102
	v_exp_f32_e32 v103, v103
	v_mfma_f32_32x32x16_bf16 v[2:17], v[74:77], v[66:69], v[2:17]
	v_exp_f32_e32 v104, v104
	v_exp_f32_e32 v105, v105
	v_mfma_f32_32x32x16_bf16 v[50:65], v[78:81], v[94:97], v[50:65]
	v_exp_f32_e32 v106, v106
	v_exp_f32_e32 v107, v107
	v_mfma_f32_32x32x16_bf16 v[34:49], v[78:81], v[146:149], v[34:49]
	v_exp_f32_e32 v108, v108
	v_exp_f32_e32 v109, v109
	v_mfma_f32_32x32x16_bf16 v[18:33], v[78:81], v[150:153], v[18:33]
	v_exp_f32_e32 v110, v110
	v_exp_f32_e32 v111, v111
	v_mfma_f32_32x32x16_bf16 v[2:17], v[78:81], v[70:73], v[2:17]
	v_exp_f32_e32 v112, v112
	v_exp_f32_e32 v113, v113
	s_and_b64 s[0:1], s[0:1], exec
	s_waitcnt vmcnt(0)
	s_cselect_b32 s14, 1, 2
	s_and_b64 s[0:1], s[40:41], exec
	s_cselect_b32 s14, s14, 0
	s_cmp_eq_u32 s14, s79
	s_waitcnt vmcnt(0)
	s_barrier
	s_cbranch_scc1 .LBB0_290
	s_cmp_eq_u32 s79, 0
	s_cselect_b64 vcc, -1, 0
	s_cmp_eq_u32 s79, 2
	s_cselect_b64 s[0:1], -1, 0
	v_cndmask_b32_e64 v66, 0, v201, s[0:1]
	s_cmp_eq_u32 s14, 2
	v_cndmask_b32_e32 v66, v66, v200, vcc
	s_cselect_b64 vcc, -1, 0
	v_cndmask_b32_e32 v67, 0, v201, vcc
	v_cndmask_b32_e64 v67, v200, v67, s[40:41]
	v_sub_f32_e32 v66, v66, v67
	v_exp_f32_e32 v66, v66
	s_nop 0
	v_pk_mul_f32 v[64:65], v[66:67], v[64:65] op_sel_hi:[0,1]
	v_pk_mul_f32 v[62:63], v[66:67], v[62:63] op_sel_hi:[0,1]
	v_pk_mul_f32 v[60:61], v[66:67], v[60:61] op_sel_hi:[0,1]
	v_pk_mul_f32 v[58:59], v[66:67], v[58:59] op_sel_hi:[0,1]
	v_pk_mul_f32 v[56:57], v[66:67], v[56:57] op_sel_hi:[0,1]
	v_pk_mul_f32 v[54:55], v[66:67], v[54:55] op_sel_hi:[0,1]
	v_pk_mul_f32 v[52:53], v[66:67], v[52:53] op_sel_hi:[0,1]
	v_pk_mul_f32 v[50:51], v[66:67], v[50:51] op_sel_hi:[0,1]
	v_pk_mul_f32 v[48:49], v[66:67], v[48:49] op_sel_hi:[0,1]
	v_pk_mul_f32 v[46:47], v[66:67], v[46:47] op_sel_hi:[0,1]
	v_pk_mul_f32 v[44:45], v[66:67], v[44:45] op_sel_hi:[0,1]
	v_pk_mul_f32 v[42:43], v[66:67], v[42:43] op_sel_hi:[0,1]
	v_pk_mul_f32 v[40:41], v[66:67], v[40:41] op_sel_hi:[0,1]
	v_pk_mul_f32 v[38:39], v[66:67], v[38:39] op_sel_hi:[0,1]
	v_pk_mul_f32 v[36:37], v[66:67], v[36:37] op_sel_hi:[0,1]
	v_pk_mul_f32 v[34:35], v[66:67], v[34:35] op_sel_hi:[0,1]
	v_pk_mul_f32 v[32:33], v[66:67], v[32:33] op_sel_hi:[0,1]
	v_pk_mul_f32 v[30:31], v[66:67], v[30:31] op_sel_hi:[0,1]
	v_pk_mul_f32 v[28:29], v[66:67], v[28:29] op_sel_hi:[0,1]
	v_pk_mul_f32 v[26:27], v[66:67], v[26:27] op_sel_hi:[0,1]
	v_pk_mul_f32 v[24:25], v[66:67], v[24:25] op_sel_hi:[0,1]
	v_pk_mul_f32 v[22:23], v[66:67], v[22:23] op_sel_hi:[0,1]
	v_pk_mul_f32 v[20:21], v[66:67], v[20:21] op_sel_hi:[0,1]
	v_pk_mul_f32 v[18:19], v[66:67], v[18:19] op_sel_hi:[0,1]
	v_pk_mul_f32 v[16:17], v[66:67], v[16:17] op_sel_hi:[0,1]
	v_pk_mul_f32 v[14:15], v[66:67], v[14:15] op_sel_hi:[0,1]
	v_pk_mul_f32 v[12:13], v[66:67], v[12:13] op_sel_hi:[0,1]
	v_pk_mul_f32 v[10:11], v[66:67], v[10:11] op_sel_hi:[0,1]
	v_pk_mul_f32 v[8:9], v[66:67], v[8:9] op_sel_hi:[0,1]
	v_pk_mul_f32 v[6:7], v[66:67], v[6:7] op_sel_hi:[0,1]
	v_pk_mul_f32 v[4:5], v[66:67], v[4:5] op_sel_hi:[0,1]
	v_pk_mul_f32 v[2:3], v[66:67], v[2:3] op_sel_hi:[0,1]
	v_mul_f32_e32 v0, v0, v66
	s_branch .LBB0_291
